# phase-1 dealing: the 112 context units 1104..1215 moved from the SSM-A blocks to blocks 144..255 (second range after their neighbourhood units)
# baseline (speedup 1.0000x reference)
.LBB0_502:
	s_mov_b32 s95, 0
	s_or_b64 exec, exec, s[6:7]
	v_mov_b32_e32 v0, s88
	v_readlane_b32 s0, v254, 17
	s_waitcnt lgkmcnt(0)
	s_barrier
	v_readlane_b32 s1, v254, 18
	v_readfirstlane_b32 s44, v0
	s_andn2_b64 vcc, exec, s[0:1]
	v_cndmask_b32_e64 v0, 0, 1, s[0:1]
	v_cmp_ne_u32_e64 s[38:39], 1, v0
	s_mov_b64 s[6:7], -1
	s_cbranch_vccnz .LBB0_613
	s_cmpk_gt_i32 s44, 0x54f
	s_cbranch_scc1 .LBB0_612
	s_lshl_b32 s0, s44, 5
	s_lshl_b32 s1, s44, 1
	s_lshl_b32 s5, s44, 7
	s_add_i32 s0, s0, 0xffff6e00
	s_addk_i32 s1, 0xfae0
	s_add_i32 s4, s44, 0xfffffd70
	s_addk_i32 s5, 0xb800
	s_add_i32 s20, s44, 0xffffff70
	s_mov_b32 s6, s44
	s_branch .LBB0_506

.LBB0_623:
	v_lshl_add_u64 v[78:79], v[84:85], 0, s[8:9]
	v_add_co_u32_e32 v66, vcc, s66, v78
	s_nop 1
	v_addc_co_u32_e32 v67, vcc, 0, v79, vcc
	global_load_dwordx4 v[66:69], v[66:67], off
	v_add_co_u32_e32 v70, vcc, s67, v78
	s_nop 1
	v_addc_co_u32_e32 v71, vcc, 0, v79, vcc
	global_load_dwordx4 v[70:73], v[70:71], off
	v_add_co_u32_e32 v74, vcc, s68, v78
	s_nop 1
	v_addc_co_u32_e32 v75, vcc, 0, v79, vcc
	global_load_dwordx4 v[74:77], v[74:75], off
	v_add_co_u32_e32 v78, vcc, s69, v78
	s_nop 1
	v_addc_co_u32_e32 v79, vcc, 0, v79, vcc
	global_load_dwordx4 v[78:81], v[78:79], off
	v_lshl_add_u64 v[94:95], v[92:93], 0, s[8:9]
	v_add_co_u32_e32 v116, vcc, s70, v94
	s_nop 1
	v_addc_co_u32_e32 v117, vcc, 0, v95, vcc
	global_load_dwordx4 v[134:137], v[116:117], off
	v_add_co_u32_e32 v116, vcc, s71, v94
	s_nop 1
	v_addc_co_u32_e32 v117, vcc, 0, v95, vcc
	global_load_dwordx4 v[138:141], v[116:117], off
	v_add_co_u32_e32 v116, vcc, s72, v94
	s_nop 1
	v_addc_co_u32_e32 v117, vcc, 0, v95, vcc
	global_load_dwordx4 v[142:145], v[116:117], off
	v_lshl_add_u64 v[116:117], v[90:91], 0, s[8:9]
	global_load_dwordx4 v[146:149], v[116:117], off
	s_add_u32 s8, s8, 64
	s_addc_u32 s9, s9, 0
	ds_read_b128 v[116:119], v0
	ds_read_b128 v[120:123], v0 offset:16
	v_add_u32_e32 v0, 0x80, v0
	s_waitcnt vmcnt(4) lgkmcnt(0)
	v_and_b32_e32 v95, 0xffff0000, v66
	v_lshlrev_b32_e32 v94, 16, v66
	s_nop 0
	v_pk_mul_f32 v[94:95], v[116:117], v[94:95]
	s_nop 0
	v_cvt_pk_bf16_f32 v66, v94, v95
	v_and_b32_e32 v95, 0xffff0000, v70
	v_lshlrev_b32_e32 v94, 16, v70
	v_pk_mul_f32 v[94:95], v[116:117], v[94:95]
	s_nop 0
	v_cvt_pk_bf16_f32 v70, v94, v95
	v_and_b32_e32 v95, 0xffff0000, v74
	v_lshlrev_b32_e32 v94, 16, v74
	v_pk_mul_f32 v[94:95], v[116:117], v[94:95]
	s_nop 0
	v_cvt_pk_bf16_f32 v74, v94, v95
	v_and_b32_e32 v95, 0xffff0000, v78
	v_lshlrev_b32_e32 v94, 16, v78
	v_pk_mul_f32 v[94:95], v[116:117], v[94:95]
	s_nop 0
	v_cvt_pk_bf16_f32 v78, v94, v95
	v_and_b32_e32 v95, 0xffff0000, v67
	v_lshlrev_b32_e32 v94, 16, v67
	v_pk_mul_f32 v[94:95], v[118:119], v[94:95]
	s_nop 0
	v_cvt_pk_bf16_f32 v67, v94, v95
	v_and_b32_e32 v95, 0xffff0000, v71
	v_lshlrev_b32_e32 v94, 16, v71
	v_pk_mul_f32 v[94:95], v[118:119], v[94:95]
	s_nop 0
	v_cvt_pk_bf16_f32 v71, v94, v95
	v_and_b32_e32 v95, 0xffff0000, v75
	v_lshlrev_b32_e32 v94, 16, v75
	v_pk_mul_f32 v[94:95], v[118:119], v[94:95]
	s_nop 0
	v_cvt_pk_bf16_f32 v75, v94, v95
	v_and_b32_e32 v95, 0xffff0000, v79
	v_lshlrev_b32_e32 v94, 16, v79
	v_pk_mul_f32 v[94:95], v[118:119], v[94:95]
	s_nop 0
	v_cvt_pk_bf16_f32 v79, v94, v95
	v_and_b32_e32 v95, 0xffff0000, v68
	v_lshlrev_b32_e32 v94, 16, v68
	v_pk_mul_f32 v[94:95], v[120:121], v[94:95]
	s_nop 0
	v_cvt_pk_bf16_f32 v68, v94, v95
	v_and_b32_e32 v95, 0xffff0000, v72
	v_lshlrev_b32_e32 v94, 16, v72
	v_pk_mul_f32 v[94:95], v[120:121], v[94:95]
	s_nop 0
	v_cvt_pk_bf16_f32 v72, v94, v95
	v_and_b32_e32 v95, 0xffff0000, v76
	v_lshlrev_b32_e32 v94, 16, v76
	v_pk_mul_f32 v[94:95], v[120:121], v[94:95]
	s_nop 0
	v_cvt_pk_bf16_f32 v76, v94, v95
	v_and_b32_e32 v95, 0xffff0000, v80
	v_lshlrev_b32_e32 v94, 16, v80
	v_pk_mul_f32 v[94:95], v[120:121], v[94:95]
	s_nop 0
	v_cvt_pk_bf16_f32 v80, v94, v95
	v_and_b32_e32 v95, 0xffff0000, v69
	v_lshlrev_b32_e32 v94, 16, v69
	v_pk_mul_f32 v[94:95], v[122:123], v[94:95]
	s_nop 0
	v_cvt_pk_bf16_f32 v69, v94, v95
	v_and_b32_e32 v95, 0xffff0000, v73
	v_lshlrev_b32_e32 v94, 16, v73
	v_pk_mul_f32 v[94:95], v[122:123], v[94:95]
	s_nop 0
	v_cvt_pk_bf16_f32 v73, v94, v95
	v_and_b32_e32 v95, 0xffff0000, v77
	v_lshlrev_b32_e32 v94, 16, v77
	v_pk_mul_f32 v[94:95], v[122:123], v[94:95]
	s_nop 0
	v_cvt_pk_bf16_f32 v77, v94, v95
	v_and_b32_e32 v95, 0xffff0000, v81
	v_lshlrev_b32_e32 v94, 16, v81
	v_pk_mul_f32 v[94:95], v[122:123], v[94:95]
	s_nop 0
	v_cvt_pk_bf16_f32 v81, v94, v95
	s_nop 1
	s_waitcnt vmcnt(3)
	v_mfma_f32_16x16x32_bf16 v[62:65], v[66:69], v[134:137], v[62:65]
	v_mfma_f32_16x16x32_bf16 v[46:49], v[70:73], v[134:137], v[46:49]
	v_mfma_f32_16x16x32_bf16 v[30:33], v[74:77], v[134:137], v[30:33]
	v_mfma_f32_16x16x32_bf16 v[14:17], v[78:81], v[134:137], v[14:17]
	s_waitcnt vmcnt(2)
	v_mfma_f32_16x16x32_bf16 v[58:61], v[66:69], v[138:141], v[58:61]
	v_mfma_f32_16x16x32_bf16 v[42:45], v[70:73], v[138:141], v[42:45]
	v_mfma_f32_16x16x32_bf16 v[26:29], v[74:77], v[138:141], v[26:29]
	v_mfma_f32_16x16x32_bf16 v[10:13], v[78:81], v[138:141], v[10:13]
	s_waitcnt vmcnt(1)
	v_mfma_f32_16x16x32_bf16 v[54:57], v[66:69], v[142:145], v[54:57]
	v_mfma_f32_16x16x32_bf16 v[38:41], v[70:73], v[142:145], v[38:41]
	v_mfma_f32_16x16x32_bf16 v[22:25], v[74:77], v[142:145], v[22:25]
	v_mfma_f32_16x16x32_bf16 v[6:9], v[78:81], v[142:145], v[6:9]
	s_waitcnt vmcnt(0)
	v_mfma_f32_16x16x32_bf16 v[50:53], v[66:69], v[146:149], v[50:53]
	v_mfma_f32_16x16x32_bf16 v[34:37], v[70:73], v[146:149], v[34:37]
	v_mfma_f32_16x16x32_bf16 v[18:21], v[74:77], v[146:149], v[18:21]
	v_mfma_f32_16x16x32_bf16 v[2:5], v[78:81], v[146:149], v[2:5]
	s_cmpk_eq_i32 s8, 0x100
	s_cbranch_scc0 .LBB0_623
	v_or_b32_e32 v0, v114, v97
	v_lshl_add_u64 v[66:67], v[0:1], 2, v[82:83]
	v_add_u32_e32 v0, v114, v97
	global_store_dword v[66:67], v62, off
	v_lshl_add_u64 v[66:67], v[0:1], 2, v[82:83]
	v_add_u32_e32 v0, v114, v98
	global_store_dword v[66:67], v63, off offset:512
	global_store_dword v[66:67], v64, off offset:1024
	global_store_dword v[66:67], v65, off offset:1536
	global_store_dword v[66:67], v58, off offset:64
	v_lshl_add_u64 v[62:63], v[0:1], 2, v[82:83]
	v_add_u32_e32 v0, v114, v99
	global_store_dword v[62:63], v59, off offset:64
	v_lshl_add_u64 v[58:59], v[0:1], 2, v[82:83]
	v_add_u32_e32 v0, v114, v100
	v_lshl_add_u64 v[64:65], v[0:1], 2, v[82:83]
	v_or_b32_e32 v0, v114, v101
	global_store_dword v[58:59], v60, off offset:64
	global_store_dword v[64:65], v61, off offset:64
	global_store_dword v[66:67], v54, off offset:128
	global_store_dword v[62:63], v55, off offset:128
	global_store_dword v[58:59], v56, off offset:128
	global_store_dword v[64:65], v57, off offset:128
	global_store_dword v[66:67], v50, off offset:192
	global_store_dword v[62:63], v51, off offset:192
	global_store_dword v[58:59], v52, off offset:192
	global_store_dword v[64:65], v53, off offset:192
	v_lshl_add_u64 v[50:51], v[0:1], 2, v[82:83]
	v_or_b32_e32 v0, v114, v102
	global_store_dword v[50:51], v46, off
	v_lshl_add_u64 v[50:51], v[0:1], 2, v[82:83]
	v_or_b32_e32 v0, v114, v103
	global_store_dword v[50:51], v47, off
	v_lshl_add_u64 v[46:47], v[0:1], 2, v[82:83]
	v_or_b32_e32 v0, v114, v104
	global_store_dword v[46:47], v48, off
	v_lshl_add_u64 v[46:47], v[0:1], 2, v[82:83]
	v_add_u32_e32 v0, v114, v101
	global_store_dword v[46:47], v49, off
	v_lshl_add_u64 v[46:47], v[0:1], 2, v[82:83]
	v_add_u32_e32 v0, v114, v102
	v_lshl_add_u64 v[48:49], v[0:1], 2, v[82:83]
	v_add_u32_e32 v0, v114, v103
	global_store_dword v[46:47], v42, off offset:64
	global_store_dword v[48:49], v43, off offset:64
	v_lshl_add_u64 v[42:43], v[0:1], 2, v[82:83]
	v_add_u32_e32 v0, v114, v104
	v_lshl_add_u64 v[50:51], v[0:1], 2, v[82:83]
	v_or_b32_e32 v0, v114, v105
	global_store_dword v[42:43], v44, off offset:64
	global_store_dword v[50:51], v45, off offset:64
	global_store_dword v[46:47], v38, off offset:128
	global_store_dword v[48:49], v39, off offset:128
	global_store_dword v[42:43], v40, off offset:128
	global_store_dword v[50:51], v41, off offset:128
	global_store_dword v[46:47], v34, off offset:192
	global_store_dword v[48:49], v35, off offset:192
	global_store_dword v[42:43], v36, off offset:192
	global_store_dword v[50:51], v37, off offset:192
	v_lshl_add_u64 v[34:35], v[0:1], 2, v[82:83]
	v_or_b32_e32 v0, v114, v106
	global_store_dword v[34:35], v30, off
	v_lshl_add_u64 v[34:35], v[0:1], 2, v[82:83]
	v_or_b32_e32 v0, v114, v107
	global_store_dword v[34:35], v31, off
	v_lshl_add_u64 v[30:31], v[0:1], 2, v[82:83]
	v_or_b32_e32 v0, v114, v108
	global_store_dword v[30:31], v32, off
	v_lshl_add_u64 v[30:31], v[0:1], 2, v[82:83]
	v_add_u32_e32 v0, v114, v105
	global_store_dword v[30:31], v33, off
	v_lshl_add_u64 v[30:31], v[0:1], 2, v[82:83]
	v_add_u32_e32 v0, v114, v106
	v_lshl_add_u64 v[32:33], v[0:1], 2, v[82:83]
	v_add_u32_e32 v0, v114, v107
	global_store_dword v[30:31], v26, off offset:64
	global_store_dword v[32:33], v27, off offset:64
	v_lshl_add_u64 v[26:27], v[0:1], 2, v[82:83]
	v_add_u32_e32 v0, v114, v108
	v_lshl_add_u64 v[34:35], v[0:1], 2, v[82:83]
	v_or_b32_e32 v0, v114, v109
	global_store_dword v[26:27], v28, off offset:64
	global_store_dword v[34:35], v29, off offset:64
	global_store_dword v[30:31], v22, off offset:128
	global_store_dword v[32:33], v23, off offset:128
	global_store_dword v[26:27], v24, off offset:128
	global_store_dword v[34:35], v25, off offset:128
	global_store_dword v[30:31], v18, off offset:192
	global_store_dword v[32:33], v19, off offset:192
	global_store_dword v[26:27], v20, off offset:192
	global_store_dword v[34:35], v21, off offset:192
	v_lshl_add_u64 v[18:19], v[0:1], 2, v[82:83]
	v_or_b32_e32 v0, v114, v110
	global_store_dword v[18:19], v14, off
	v_lshl_add_u64 v[18:19], v[0:1], 2, v[82:83]
	v_or_b32_e32 v0, v114, v111
	global_store_dword v[18:19], v15, off
	v_lshl_add_u64 v[14:15], v[0:1], 2, v[82:83]
	v_or_b32_e32 v0, v114, v112
	global_store_dword v[14:15], v16, off
	v_lshl_add_u64 v[14:15], v[0:1], 2, v[82:83]
	v_add_u32_e32 v0, v114, v109
	global_store_dword v[14:15], v17, off
	v_lshl_add_u64 v[14:15], v[0:1], 2, v[82:83]
	v_add_u32_e32 v0, v114, v110
	v_lshl_add_u64 v[16:17], v[0:1], 2, v[82:83]
	v_add_u32_e32 v0, v114, v111
	global_store_dword v[14:15], v10, off offset:64
	global_store_dword v[16:17], v11, off offset:64
	v_lshl_add_u64 v[10:11], v[0:1], 2, v[82:83]
	v_add_u32_e32 v0, v114, v112
	v_lshl_add_u64 v[18:19], v[0:1], 2, v[82:83]
	s_mov_b32 s0, 64
	s_mov_b64 s[8:9], 0
	s_and_b64 vcc, exec, s[6:7]
	global_store_dword v[10:11], v12, off offset:64
	global_store_dword v[18:19], v13, off offset:64
	global_store_dword v[14:15], v6, off offset:128
	global_store_dword v[16:17], v7, off offset:128
	global_store_dword v[10:11], v8, off offset:128
	global_store_dword v[18:19], v9, off offset:128
	global_store_dword v[14:15], v2, off offset:192
	global_store_dword v[16:17], v3, off offset:192
	global_store_dword v[10:11], v4, off offset:192
	global_store_dword v[18:19], v5, off offset:192
	s_cbranch_vccz .LBB0_622
	s_movk_i32 s4, 0x2a0
	s_movk_i32 s0, 0x450
	s_movk_i32 s1, 0x90
	s_waitcnt lgkmcnt(0)
	s_barrier
	s_add_i32 s4, s44, s4
	s_cmp_ge_i32 s4, s0
	s_cbranch_scc0 .LBB0_627
	s_branch .LBB0_727

.Lwa_done:
	s_barrier
	s_sub_u32 s4, s40, 144
	s_add_u32 s4, s4, 0x200
	s_movk_i32 s0, 0x2a0
	s_movk_i32 s1, 0x70
	s_mov_b32 s95, 1
	s_branch .LBB0_627

.LBB0_727:
	s_cmp_eq_u32 s95, 1
	s_cbranch_scc0 .Lp1_done
	s_mov_b32 s95, 0
	v_readlane_b32 s4, v254, 33
	s_addk_i32 s4, 0x3c0
	s_movk_i32 s0, 0x4c0
	s_movk_i32 s1, 0x70
	s_branch .LBB0_627
